# up GEMM: conv weights/biases prefetched into LDS by LDS-DMA before the unit K loop; fused epilogue reads them with ds_read_b128 instead of 16 global loads
# speedup vs baseline: 1.0281x; 1.0021x over previous
.LBB0_78:
	v_readlane_b32 s5, v253, 30
	s_cmp_gt_u32 s5, 3
	s_cbranch_scc1 .Lwpf_skip
	s_movk_i32 s19, 0xb8
	s_mov_b32 s24, 0x10800
	s_cmp_eq_u32 s5, 3
	s_cselect_b32 s19, 0xc0, s19
	s_load_dwordx2 s[22:23], s[54:55], s19
	v_readlane_b32 s21, v253, 41
	s_cselect_b32 s24, 0x5800, s24
	s_mul_i32 s21, s21, s24
	s_cselect_b32 s24, 0, s5
	s_mulk_i32 s24, 0x5800
	s_add_u32 s21, s21, s24
	s_lshl_b32 s24, s26, 9
	s_add_u32 s21, s21, s24
	s_and_b32 s24, s59, 1
	s_lshl_b32 s24, s24, 12
	s_lshl_b32 s25, s5, 10
	s_add_u32 s24, s24, s25
	s_add_u32 s24, s24, 0x21000
	s_mov_b32 m0, s24
	v_mbcnt_lo_u32_b32 v6, -1, 0
	v_mbcnt_hi_u32_b32 v6, -1, v6
	v_and_b32_e32 v7, 31, v6
	v_lshlrev_b32_e32 v7, 4, v7
	v_lshrrev_b32_e32 v6, 5, v6
	v_mul_u32_u24_e32 v6, 0x2c00, v6
	v_add_u32_e32 v6, v6, v7
	v_mov_b32_e32 v7, 0
	s_waitcnt lgkmcnt(0)
	s_add_u32 s22, s22, s21
	s_addc_u32 s23, s23, 0
	v_lshl_add_u64 v[6:7], s[22:23], 0, v[6:7]
	s_nop 0
	global_load_lds_dwordx4 v[6:7], off

.LBB0_82:
	s_cmp_gt_i32 s4, 63
	s_cbranch_scc1 .Lup_raw_epi
	v_mbcnt_lo_u32_b32 v142, -1, 0
	v_mbcnt_hi_u32_b32 v142, -1, v142
	v_and_b32_e32 v143, 3, v142
	v_lshrrev_b32_e32 v144, 2, v142
	v_lshl_or_b32 v145, v143, 4, v144
	v_lshlrev_b32_e32 v145, 2, v145
	s_lshl_b32 s19, s4, 8
	s_add_i32 s19, s19, s43
	s_lshl_b32 s26, s26, 7
	v_add_u32_e32 v224, s26, v149
	v_lshlrev_b32_e32 v226, 2, v224
	v_mov_b32_e32 v227, 0
	s_and_b32 s27, s59, 1
	s_lshl_b32 s27, s27, 12
	s_add_u32 s27, s27, 0x21000
	v_lshl_add_u32 v225, v149, 2, s27
	ds_read_b128 v[152:155], v225
	ds_read_b128 v[156:159], v225 offset:16
	ds_read_b128 v[184:187], v225 offset:512
	ds_read_b128 v[188:191], v225 offset:528
	ds_read_b128 v[160:163], v225 offset:1024
	ds_read_b128 v[164:167], v225 offset:1040
	ds_read_b128 v[192:195], v225 offset:1536
	ds_read_b128 v[196:199], v225 offset:1552
	ds_read_b128 v[168:171], v225 offset:2048
	ds_read_b128 v[172:175], v225 offset:2064
	ds_read_b128 v[200:203], v225 offset:2560
	ds_read_b128 v[204:207], v225 offset:2576
	ds_read_b128 v[176:179], v225 offset:3072
	ds_read_b128 v[180:183], v225 offset:3088
	ds_read_b128 v[208:211], v225 offset:3584
	ds_read_b128 v[212:215], v225 offset:3600
	v_lshl_add_u32 v228, v144, 2, s19
	v_and_b32_e32 v229, 0x60, v149
	v_lshl_or_b32 v229, v143, 3, v229
	v_add_u32_e32 v229, s26, v229
	v_mov_b64_e32 v[146:147], s[10:11]
	s_movk_i32 s27, 0x1600
	v_mad_u64_u32 v[216:217], s[4:5], v228, s27, v[146:147]
	v_lshlrev_b32_e32 v229, 1, v229
	v_mov_b32_e32 v228, v229
	v_mov_b32_e32 v229, 0
	v_lshl_add_u64 v[216:217], v[216:217], 0, v[228:229]
	s_and_b32 s27, s19, 0x1fc0
	s_cmpk_lg_u32 s27, 0x1f40
	s_cbranch_scc1 .Lup_f_notail
	v_cmp_eq_u32_e32 vcc, 15, v5
	s_and_saveexec_b64 s[4:5], vcc
	v_lshl_add_u32 v228, v5, 2, s19
	v_add_u32_e32 v229, 130, v228
	v_lshrrev_b32_e32 v225, 13, v229
	v_and_b32_e32 v229, 0x1fff, v229
	v_lshl_add_u32 v229, v225, 1, v229
	v_add_u32_e32 v229, 0xffffe002, v229
	v_mov_b64_e32 v[146:147], s[12:13]
	v_mad_u64_u32 v[146:147], s[28:29], v229, s90, v[146:147]
	v_lshl_add_u64 v[146:147], v[146:147], 0, v[226:227]
	global_store_dwordx4 v[146:147], v[34:37], off
	global_store_dwordx4 v[146:147], v[30:33], off offset:16
	v_add_co_u32_e32 v146, vcc, 0x2c00, v146
	v_addc_co_u32_e32 v147, vcc, 0, v147, vcc
	global_store_dwordx4 v[146:147], v[26:29], off
	global_store_dwordx4 v[146:147], v[22:25], off offset:16
	v_add_u32_e32 v229, 131, v228
	v_lshrrev_b32_e32 v225, 13, v229
	v_and_b32_e32 v229, 0x1fff, v229
	v_lshl_add_u32 v229, v225, 1, v229
	v_add_u32_e32 v229, 0xffffe002, v229
	v_mov_b64_e32 v[146:147], s[12:13]
	v_mad_u64_u32 v[146:147], s[28:29], v229, s90, v[146:147]
	v_lshl_add_u64 v[146:147], v[146:147], 0, v[226:227]
	global_store_dwordx4 v[146:147], v[18:21], off
	global_store_dwordx4 v[146:147], v[14:17], off offset:16
	v_add_co_u32_e32 v146, vcc, 0x2c00, v146
	v_addc_co_u32_e32 v147, vcc, 0, v147, vcc
	global_store_dwordx4 v[146:147], v[10:13], off
	global_store_dwordx4 v[146:147], v[6:9], off offset:16
	s_or_b64 exec, exec, s[4:5]
	s_waitcnt vmcnt(0)
.Lup_f_notail:
	s_add_u32 s30, s10, 0x6000000
	s_addc_u32 s31, s11, 0
	v_lshlrev_b32_e32 v228, 1, v224
	v_mov_b32_e32 v229, 0
	v_lshl_add_u64 v[228:229], s[30:31], 0, v[228:229]
	s_lshr_b32 s27, s19, 6
	s_mul_i32 s27, s27, 0xb000
	v_cvt_pk_bf16_f32 v242, v130, v131
	v_cvt_pk_bf16_f32 v243, v132, v133
	v_cvt_pk_bf16_f32 v244, v126, v127
	v_cvt_pk_bf16_f32 v245, v128, v129
	v_cvt_pk_bf16_f32 v246, v122, v123
	v_cvt_pk_bf16_f32 v247, v124, v125
	v_cvt_pk_bf16_f32 v248, v118, v119
	v_cvt_pk_bf16_f32 v249, v120, v121
	s_mov_b32 exec_lo, 0x00010001
	s_mov_b32 exec_hi, 0x00010001
	s_add_u32 s28, s27, 0x0
	s_mov_b32 s29, 0
	v_lshl_add_u64 v[146:147], v[228:229], 0, s[28:29]
	global_store_dwordx4 v[146:147], v[242:245], off
	s_add_u32 s28, s28, 0x1600
	v_lshl_add_u64 v[146:147], v[228:229], 0, s[28:29]
	global_store_dwordx4 v[146:147], v[246:249], off
	v_cvt_pk_bf16_f32 v242, v114, v115
	v_cvt_pk_bf16_f32 v243, v116, v117
	v_cvt_pk_bf16_f32 v244, v110, v111
	v_cvt_pk_bf16_f32 v245, v112, v113
	v_cvt_pk_bf16_f32 v246, v106, v107
	v_cvt_pk_bf16_f32 v247, v108, v109
	v_cvt_pk_bf16_f32 v248, v102, v103
	v_cvt_pk_bf16_f32 v249, v104, v105
	s_add_u32 s28, s27, 0x2c00
	s_mov_b32 s29, 0
	v_lshl_add_u64 v[146:147], v[228:229], 0, s[28:29]
	global_store_dwordx4 v[146:147], v[242:245], off
	s_add_u32 s28, s28, 0x1600
	v_lshl_add_u64 v[146:147], v[228:229], 0, s[28:29]
	global_store_dwordx4 v[146:147], v[246:249], off
	s_mov_b64 exec, -1
	v_cvt_pk_bf16_f32 v242, v98, v99
	v_cvt_pk_bf16_f32 v243, v100, v101
	v_cvt_pk_bf16_f32 v244, v94, v95
	v_cvt_pk_bf16_f32 v245, v96, v97
	v_cvt_pk_bf16_f32 v246, v90, v91
	v_cvt_pk_bf16_f32 v247, v92, v93
	v_cvt_pk_bf16_f32 v248, v86, v87
	v_cvt_pk_bf16_f32 v249, v88, v89
	s_mov_b32 exec_lo, 0x80008000
	s_mov_b32 exec_hi, 0x80008000
	s_add_u32 s28, s27, 0x5800
	s_mov_b32 s29, 0
	v_lshl_add_u64 v[146:147], v[228:229], 0, s[28:29]
	global_store_dwordx4 v[146:147], v[242:245], off
	s_add_u32 s28, s28, 0x1600
	v_lshl_add_u64 v[146:147], v[228:229], 0, s[28:29]
	global_store_dwordx4 v[146:147], v[246:249], off
	v_cvt_pk_bf16_f32 v242, v82, v83
	v_cvt_pk_bf16_f32 v243, v84, v85
	v_cvt_pk_bf16_f32 v244, v78, v79
	v_cvt_pk_bf16_f32 v245, v80, v81
	v_cvt_pk_bf16_f32 v246, v74, v75
	v_cvt_pk_bf16_f32 v247, v76, v77
	v_cvt_pk_bf16_f32 v248, v70, v71
	v_cvt_pk_bf16_f32 v249, v72, v73
	s_add_u32 s28, s27, 0x8400
	s_mov_b32 s29, 0
	v_lshl_add_u64 v[146:147], v[228:229], 0, s[28:29]
	global_store_dwordx4 v[146:147], v[242:245], off
	s_add_u32 s28, s28, 0x1600
	v_lshl_add_u64 v[146:147], v[228:229], 0, s[28:29]
	global_store_dwordx4 v[146:147], v[246:249], off
	s_mov_b64 exec, -1
	v_cvt_pk_bf16_f32 v242, v66, v67
	v_cvt_pk_bf16_f32 v243, v68, v69
	v_cvt_pk_bf16_f32 v244, v62, v63
	v_cvt_pk_bf16_f32 v245, v64, v65
	v_cvt_pk_bf16_f32 v246, v58, v59
	v_cvt_pk_bf16_f32 v247, v60, v61
	v_cvt_pk_bf16_f32 v248, v54, v55
	v_cvt_pk_bf16_f32 v249, v56, v57
	s_mov_b32 exec_lo, 0x00010001
	s_mov_b32 exec_hi, 0x00010001
	s_add_u32 s28, s27, 0x16000
	s_mov_b32 s29, 0
	v_lshl_add_u64 v[146:147], v[228:229], 0, s[28:29]
	global_store_dwordx4 v[146:147], v[242:245], off
	s_add_u32 s28, s28, 0x1600
	v_lshl_add_u64 v[146:147], v[228:229], 0, s[28:29]
	global_store_dwordx4 v[146:147], v[246:249], off
	v_cvt_pk_bf16_f32 v242, v50, v51
	v_cvt_pk_bf16_f32 v243, v52, v53
	v_cvt_pk_bf16_f32 v244, v46, v47
	v_cvt_pk_bf16_f32 v245, v48, v49
	v_cvt_pk_bf16_f32 v246, v42, v43
	v_cvt_pk_bf16_f32 v247, v44, v45
	v_cvt_pk_bf16_f32 v248, v38, v39
	v_cvt_pk_bf16_f32 v249, v40, v41
	s_add_u32 s28, s27, 0x18c00
	s_mov_b32 s29, 0
	v_lshl_add_u64 v[146:147], v[228:229], 0, s[28:29]
	global_store_dwordx4 v[146:147], v[242:245], off
	s_add_u32 s28, s28, 0x1600
	v_lshl_add_u64 v[146:147], v[228:229], 0, s[28:29]
	global_store_dwordx4 v[146:147], v[246:249], off
	s_mov_b64 exec, -1
	v_cvt_pk_bf16_f32 v242, v34, v35
	v_cvt_pk_bf16_f32 v243, v36, v37
	v_cvt_pk_bf16_f32 v244, v30, v31
	v_cvt_pk_bf16_f32 v245, v32, v33
	v_cvt_pk_bf16_f32 v246, v26, v27
	v_cvt_pk_bf16_f32 v247, v28, v29
	v_cvt_pk_bf16_f32 v248, v22, v23
	v_cvt_pk_bf16_f32 v249, v24, v25
	s_mov_b32 exec_lo, 0x80008000
	s_mov_b32 exec_hi, 0x80008000
	s_add_u32 s28, s27, 0x1b800
	s_mov_b32 s29, 0
	v_lshl_add_u64 v[146:147], v[228:229], 0, s[28:29]
	global_store_dwordx4 v[146:147], v[242:245], off
	s_add_u32 s28, s28, 0x1600
	v_lshl_add_u64 v[146:147], v[228:229], 0, s[28:29]
	global_store_dwordx4 v[146:147], v[246:249], off
	v_cvt_pk_bf16_f32 v242, v18, v19
	v_cvt_pk_bf16_f32 v243, v20, v21
	v_cvt_pk_bf16_f32 v244, v14, v15
	v_cvt_pk_bf16_f32 v245, v16, v17
	v_cvt_pk_bf16_f32 v246, v10, v11
	v_cvt_pk_bf16_f32 v247, v12, v13
	v_cvt_pk_bf16_f32 v248, v6, v7
	v_cvt_pk_bf16_f32 v249, v8, v9
	s_add_u32 s28, s27, 0x1e400
	s_mov_b32 s29, 0
	v_lshl_add_u64 v[146:147], v[228:229], 0, s[28:29]
	global_store_dwordx4 v[146:147], v[242:245], off
	s_add_u32 s28, s28, 0x1600
	v_lshl_add_u64 v[146:147], v[228:229], 0, s[28:29]
	global_store_dwordx4 v[146:147], v[246:249], off
	s_mov_b64 exec, -1
	s_mov_b32 s30, 0xbfb8aa3b
	s_mov_b32 s31, 0xbfb8aa3b
	s_waitcnt lgkmcnt(0)
	v_pk_fma_f32 v[220:221], v[130:131], v[168:169], v[176:177]
	v_pk_fma_f32 v[222:223], v[114:115], v[168:169], v[176:177]
	v_fmac_f32_dpp v220, v82, v160 row_shr:1 row_mask:0xf bank_mask:0xf
	v_fmac_f32_dpp v220, v98, v152 row_shr:1 row_mask:0xf bank_mask:0xf
	v_fmac_f32_dpp v222, v82, v152 row_shr:1 row_mask:0xf bank_mask:0xf
	v_fmac_f32_dpp v221, v83, v161 row_shr:1 row_mask:0xf bank_mask:0xf
	v_fmac_f32_dpp v221, v99, v153 row_shr:1 row_mask:0xf bank_mask:0xf
	v_fmac_f32_dpp v223, v83, v153 row_shr:1 row_mask:0xf bank_mask:0xf
	v_pk_fma_f32 v[222:223], v[130:131], v[160:161], v[222:223]
	v_pk_fma_f32 v[82:83], v[82:83], v[168:169], v[176:177]
	v_pk_fma_f32 v[82:83], v[98:99], v[160:161], v[82:83]
	v_pk_fma_f32 v[82:83], v[114:115], v[152:153], v[82:83]
	v_pk_fma_f32 v[98:99], v[98:99], v[168:169], v[176:177]
	v_pk_fma_f32 v[98:99], v[114:115], v[160:161], v[98:99]
	v_pk_fma_f32 v[98:99], v[130:131], v[152:153], v[98:99]
	v_mov_b32_e32 v130, v220
	v_mov_b32_e32 v131, v221
	v_mov_b32_e32 v114, v222
	v_mov_b32_e32 v115, v223
	v_pk_fma_f32 v[220:221], v[132:133], v[170:171], v[178:179]
	v_pk_fma_f32 v[222:223], v[116:117], v[170:171], v[178:179]
	v_fmac_f32_dpp v220, v84, v162 row_shr:1 row_mask:0xf bank_mask:0xf
	v_fmac_f32_dpp v220, v100, v154 row_shr:1 row_mask:0xf bank_mask:0xf
	v_fmac_f32_dpp v222, v84, v154 row_shr:1 row_mask:0xf bank_mask:0xf
	v_fmac_f32_dpp v221, v85, v163 row_shr:1 row_mask:0xf bank_mask:0xf
	v_fmac_f32_dpp v221, v101, v155 row_shr:1 row_mask:0xf bank_mask:0xf
	v_fmac_f32_dpp v223, v85, v155 row_shr:1 row_mask:0xf bank_mask:0xf
	v_pk_fma_f32 v[222:223], v[132:133], v[162:163], v[222:223]
	v_pk_fma_f32 v[84:85], v[84:85], v[170:171], v[178:179]
	v_pk_fma_f32 v[84:85], v[100:101], v[162:163], v[84:85]
	v_pk_fma_f32 v[84:85], v[116:117], v[154:155], v[84:85]
	v_pk_fma_f32 v[100:101], v[100:101], v[170:171], v[178:179]
	v_pk_fma_f32 v[100:101], v[116:117], v[162:163], v[100:101]
	v_pk_fma_f32 v[100:101], v[132:133], v[154:155], v[100:101]
	v_mov_b32_e32 v132, v220
	v_mov_b32_e32 v133, v221
	v_mov_b32_e32 v116, v222
	v_mov_b32_e32 v117, v223
	v_pk_fma_f32 v[220:221], v[126:127], v[172:173], v[180:181]
	v_pk_fma_f32 v[222:223], v[110:111], v[172:173], v[180:181]
	v_fmac_f32_dpp v220, v78, v164 row_shr:1 row_mask:0xf bank_mask:0xf
	v_fmac_f32_dpp v220, v94, v156 row_shr:1 row_mask:0xf bank_mask:0xf
	v_fmac_f32_dpp v222, v78, v156 row_shr:1 row_mask:0xf bank_mask:0xf
	v_fmac_f32_dpp v221, v79, v165 row_shr:1 row_mask:0xf bank_mask:0xf
	v_fmac_f32_dpp v221, v95, v157 row_shr:1 row_mask:0xf bank_mask:0xf
	v_fmac_f32_dpp v223, v79, v157 row_shr:1 row_mask:0xf bank_mask:0xf
	v_pk_fma_f32 v[222:223], v[126:127], v[164:165], v[222:223]
	v_pk_fma_f32 v[78:79], v[78:79], v[172:173], v[180:181]
	v_pk_fma_f32 v[78:79], v[94:95], v[164:165], v[78:79]
	v_pk_fma_f32 v[78:79], v[110:111], v[156:157], v[78:79]
	v_pk_fma_f32 v[94:95], v[94:95], v[172:173], v[180:181]
	v_pk_fma_f32 v[94:95], v[110:111], v[164:165], v[94:95]
	v_pk_fma_f32 v[94:95], v[126:127], v[156:157], v[94:95]
	v_mov_b32_e32 v126, v220
	v_mov_b32_e32 v127, v221
	v_mov_b32_e32 v110, v222
	v_mov_b32_e32 v111, v223
	v_pk_fma_f32 v[220:221], v[128:129], v[174:175], v[182:183]
	v_pk_fma_f32 v[222:223], v[112:113], v[174:175], v[182:183]
	v_fmac_f32_dpp v220, v80, v166 row_shr:1 row_mask:0xf bank_mask:0xf
	v_fmac_f32_dpp v220, v96, v158 row_shr:1 row_mask:0xf bank_mask:0xf
	v_fmac_f32_dpp v222, v80, v158 row_shr:1 row_mask:0xf bank_mask:0xf
	v_fmac_f32_dpp v221, v81, v167 row_shr:1 row_mask:0xf bank_mask:0xf
	v_fmac_f32_dpp v221, v97, v159 row_shr:1 row_mask:0xf bank_mask:0xf
	v_fmac_f32_dpp v223, v81, v159 row_shr:1 row_mask:0xf bank_mask:0xf
	v_pk_fma_f32 v[222:223], v[128:129], v[166:167], v[222:223]
	v_pk_fma_f32 v[80:81], v[80:81], v[174:175], v[182:183]
	v_pk_fma_f32 v[80:81], v[96:97], v[166:167], v[80:81]
	v_pk_fma_f32 v[80:81], v[112:113], v[158:159], v[80:81]
	v_pk_fma_f32 v[96:97], v[96:97], v[174:175], v[182:183]
	v_pk_fma_f32 v[96:97], v[112:113], v[166:167], v[96:97]
	v_pk_fma_f32 v[96:97], v[128:129], v[158:159], v[96:97]
	v_mov_b32_e32 v128, v220
	v_mov_b32_e32 v129, v221
	v_mov_b32_e32 v112, v222
	v_mov_b32_e32 v113, v223
	v_pk_fma_f32 v[220:221], v[122:123], v[200:201], v[208:209]
	v_pk_fma_f32 v[222:223], v[106:107], v[200:201], v[208:209]
	v_fmac_f32_dpp v220, v74, v192 row_shr:1 row_mask:0xf bank_mask:0xf
	v_fmac_f32_dpp v220, v90, v184 row_shr:1 row_mask:0xf bank_mask:0xf
	v_fmac_f32_dpp v222, v74, v184 row_shr:1 row_mask:0xf bank_mask:0xf
	v_fmac_f32_dpp v221, v75, v193 row_shr:1 row_mask:0xf bank_mask:0xf
	v_fmac_f32_dpp v221, v91, v185 row_shr:1 row_mask:0xf bank_mask:0xf
	v_fmac_f32_dpp v223, v75, v185 row_shr:1 row_mask:0xf bank_mask:0xf
	v_pk_fma_f32 v[222:223], v[122:123], v[192:193], v[222:223]
	v_pk_fma_f32 v[74:75], v[74:75], v[200:201], v[208:209]
	v_pk_fma_f32 v[74:75], v[90:91], v[192:193], v[74:75]
	v_pk_fma_f32 v[74:75], v[106:107], v[184:185], v[74:75]
	v_pk_fma_f32 v[90:91], v[90:91], v[200:201], v[208:209]
	v_pk_fma_f32 v[90:91], v[106:107], v[192:193], v[90:91]
	v_pk_fma_f32 v[90:91], v[122:123], v[184:185], v[90:91]
	v_mov_b32_e32 v122, v220
	v_mov_b32_e32 v123, v221
	v_mov_b32_e32 v106, v222
	v_mov_b32_e32 v107, v223
	v_pk_fma_f32 v[220:221], v[124:125], v[202:203], v[210:211]
	v_pk_fma_f32 v[222:223], v[108:109], v[202:203], v[210:211]
	v_fmac_f32_dpp v220, v76, v194 row_shr:1 row_mask:0xf bank_mask:0xf
	v_fmac_f32_dpp v220, v92, v186 row_shr:1 row_mask:0xf bank_mask:0xf
	v_fmac_f32_dpp v222, v76, v186 row_shr:1 row_mask:0xf bank_mask:0xf
	v_fmac_f32_dpp v221, v77, v195 row_shr:1 row_mask:0xf bank_mask:0xf
	v_fmac_f32_dpp v221, v93, v187 row_shr:1 row_mask:0xf bank_mask:0xf
	v_fmac_f32_dpp v223, v77, v187 row_shr:1 row_mask:0xf bank_mask:0xf
	v_pk_fma_f32 v[222:223], v[124:125], v[194:195], v[222:223]
	v_pk_fma_f32 v[76:77], v[76:77], v[202:203], v[210:211]
	v_pk_fma_f32 v[76:77], v[92:93], v[194:195], v[76:77]
	v_pk_fma_f32 v[76:77], v[108:109], v[186:187], v[76:77]
	v_pk_fma_f32 v[92:93], v[92:93], v[202:203], v[210:211]
	v_pk_fma_f32 v[92:93], v[108:109], v[194:195], v[92:93]
	v_pk_fma_f32 v[92:93], v[124:125], v[186:187], v[92:93]
	v_mov_b32_e32 v124, v220
	v_mov_b32_e32 v125, v221
	v_mov_b32_e32 v108, v222
	v_mov_b32_e32 v109, v223
	v_pk_fma_f32 v[220:221], v[118:119], v[204:205], v[212:213]
	v_pk_fma_f32 v[222:223], v[102:103], v[204:205], v[212:213]
	v_fmac_f32_dpp v220, v70, v196 row_shr:1 row_mask:0xf bank_mask:0xf
	v_fmac_f32_dpp v220, v86, v188 row_shr:1 row_mask:0xf bank_mask:0xf
	v_fmac_f32_dpp v222, v70, v188 row_shr:1 row_mask:0xf bank_mask:0xf
	v_fmac_f32_dpp v221, v71, v197 row_shr:1 row_mask:0xf bank_mask:0xf
	v_fmac_f32_dpp v221, v87, v189 row_shr:1 row_mask:0xf bank_mask:0xf
	v_fmac_f32_dpp v223, v71, v189 row_shr:1 row_mask:0xf bank_mask:0xf
	v_pk_fma_f32 v[222:223], v[118:119], v[196:197], v[222:223]
	v_pk_fma_f32 v[70:71], v[70:71], v[204:205], v[212:213]
	v_pk_fma_f32 v[70:71], v[86:87], v[196:197], v[70:71]
	v_pk_fma_f32 v[70:71], v[102:103], v[188:189], v[70:71]
	v_pk_fma_f32 v[86:87], v[86:87], v[204:205], v[212:213]
	v_pk_fma_f32 v[86:87], v[102:103], v[196:197], v[86:87]
	v_pk_fma_f32 v[86:87], v[118:119], v[188:189], v[86:87]
	v_mov_b32_e32 v118, v220
	v_mov_b32_e32 v119, v221
	v_mov_b32_e32 v102, v222
	v_mov_b32_e32 v103, v223
	v_pk_fma_f32 v[220:221], v[120:121], v[206:207], v[214:215]
	v_pk_fma_f32 v[222:223], v[104:105], v[206:207], v[214:215]
	v_fmac_f32_dpp v220, v72, v198 row_shr:1 row_mask:0xf bank_mask:0xf
	v_fmac_f32_dpp v220, v88, v190 row_shr:1 row_mask:0xf bank_mask:0xf
	v_fmac_f32_dpp v222, v72, v190 row_shr:1 row_mask:0xf bank_mask:0xf
	v_fmac_f32_dpp v221, v73, v199 row_shr:1 row_mask:0xf bank_mask:0xf
	v_fmac_f32_dpp v221, v89, v191 row_shr:1 row_mask:0xf bank_mask:0xf
	v_fmac_f32_dpp v223, v73, v191 row_shr:1 row_mask:0xf bank_mask:0xf
	v_pk_fma_f32 v[222:223], v[120:121], v[198:199], v[222:223]
	v_pk_fma_f32 v[72:73], v[72:73], v[206:207], v[214:215]
	v_pk_fma_f32 v[72:73], v[88:89], v[198:199], v[72:73]
	v_pk_fma_f32 v[72:73], v[104:105], v[190:191], v[72:73]
	v_pk_fma_f32 v[88:89], v[88:89], v[206:207], v[214:215]
	v_pk_fma_f32 v[88:89], v[104:105], v[198:199], v[88:89]
	v_pk_fma_f32 v[88:89], v[120:121], v[190:191], v[88:89]
	v_mov_b32_e32 v120, v220
	v_mov_b32_e32 v121, v221
	v_mov_b32_e32 v104, v222
	v_mov_b32_e32 v105, v223
	v_pk_mul_f32 v[220:221], v[130:131], s[30:31]
	v_exp_f32_e32 v220, v220
	v_exp_f32_e32 v221, v221
	s_nop 0
	v_pk_add_f32 v[220:221], v[220:221], 1.0 op_sel_hi:[1,0]
	v_rcp_f32_e32 v220, v220
	v_rcp_f32_e32 v221, v221
	s_nop 0
	v_pk_mul_f32 v[220:221], v[220:221], v[130:131]
	v_pk_mul_f32 v[220:221], v[220:221], v[122:123]
	v_cvt_pk_bf16_f32 v224, v220, v221
	v_pk_mul_f32 v[220:221], v[132:133], s[30:31]
	v_exp_f32_e32 v220, v220
	v_exp_f32_e32 v221, v221
	s_nop 0
	v_pk_add_f32 v[220:221], v[220:221], 1.0 op_sel_hi:[1,0]
	v_rcp_f32_e32 v220, v220
	v_rcp_f32_e32 v221, v221
	s_nop 0
	v_pk_mul_f32 v[220:221], v[220:221], v[132:133]
	v_pk_mul_f32 v[220:221], v[220:221], v[124:125]
	v_cvt_pk_bf16_f32 v225, v220, v221
	v_pk_mul_f32 v[220:221], v[126:127], s[30:31]
	v_exp_f32_e32 v220, v220
	v_exp_f32_e32 v221, v221
	s_nop 0
	v_pk_add_f32 v[220:221], v[220:221], 1.0 op_sel_hi:[1,0]
	v_rcp_f32_e32 v220, v220
	v_rcp_f32_e32 v221, v221
	s_nop 0
	v_pk_mul_f32 v[220:221], v[220:221], v[126:127]
	v_pk_mul_f32 v[220:221], v[220:221], v[118:119]
	v_cvt_pk_bf16_f32 v226, v220, v221
	v_pk_mul_f32 v[220:221], v[128:129], s[30:31]
	v_exp_f32_e32 v220, v220
	v_exp_f32_e32 v221, v221
	s_nop 0
	v_pk_add_f32 v[220:221], v[220:221], 1.0 op_sel_hi:[1,0]
	v_rcp_f32_e32 v220, v220
	v_rcp_f32_e32 v221, v221
	s_nop 0
	v_pk_mul_f32 v[220:221], v[220:221], v[128:129]
	v_pk_mul_f32 v[220:221], v[220:221], v[120:121]
	v_cvt_pk_bf16_f32 v227, v220, v221
	ds_bpermute_b32 v242, v145, v224
	ds_bpermute_b32 v243, v145, v225
	ds_bpermute_b32 v244, v145, v226
	ds_bpermute_b32 v245, v145, v227
	s_mov_b32 s4, 0x0
	s_mov_b32 s5, 0
	v_lshl_add_u64 v[146:147], v[216:217], 0, s[4:5]
	v_pk_mul_f32 v[220:221], v[114:115], s[30:31]
	v_exp_f32_e32 v220, v220
	v_exp_f32_e32 v221, v221
	s_nop 0
	v_pk_add_f32 v[220:221], v[220:221], 1.0 op_sel_hi:[1,0]
	v_rcp_f32_e32 v220, v220
	v_rcp_f32_e32 v221, v221
	s_nop 0
	v_pk_mul_f32 v[220:221], v[220:221], v[114:115]
	v_pk_mul_f32 v[220:221], v[220:221], v[106:107]
	v_cvt_pk_bf16_f32 v224, v220, v221
	v_pk_mul_f32 v[220:221], v[116:117], s[30:31]
	v_exp_f32_e32 v220, v220
	v_exp_f32_e32 v221, v221
	s_nop 0
	v_pk_add_f32 v[220:221], v[220:221], 1.0 op_sel_hi:[1,0]
	v_rcp_f32_e32 v220, v220
	v_rcp_f32_e32 v221, v221
	s_nop 0
	v_pk_mul_f32 v[220:221], v[220:221], v[116:117]
	v_pk_mul_f32 v[220:221], v[220:221], v[108:109]
	v_cvt_pk_bf16_f32 v225, v220, v221
	v_pk_mul_f32 v[220:221], v[110:111], s[30:31]
	v_exp_f32_e32 v220, v220
	v_exp_f32_e32 v221, v221
	s_nop 0
	v_pk_add_f32 v[220:221], v[220:221], 1.0 op_sel_hi:[1,0]
	v_rcp_f32_e32 v220, v220
	v_rcp_f32_e32 v221, v221
	s_nop 0
	v_pk_mul_f32 v[220:221], v[220:221], v[110:111]
	v_pk_mul_f32 v[220:221], v[220:221], v[102:103]
	v_cvt_pk_bf16_f32 v226, v220, v221
	v_pk_mul_f32 v[220:221], v[112:113], s[30:31]
	v_exp_f32_e32 v220, v220
	v_exp_f32_e32 v221, v221
	s_nop 0
	v_pk_add_f32 v[220:221], v[220:221], 1.0 op_sel_hi:[1,0]
	v_rcp_f32_e32 v220, v220
	v_rcp_f32_e32 v221, v221
	s_nop 0
	v_pk_mul_f32 v[220:221], v[220:221], v[112:113]
	v_pk_mul_f32 v[220:221], v[220:221], v[104:105]
	v_cvt_pk_bf16_f32 v227, v220, v221
	ds_bpermute_b32 v246, v145, v224
	ds_bpermute_b32 v247, v145, v225
	ds_bpermute_b32 v248, v145, v226
	ds_bpermute_b32 v249, v145, v227
	s_mov_b32 s4, 0x1600
	s_mov_b32 s5, 0
	v_lshl_add_u64 v[228:229], v[216:217], 0, s[4:5]
	s_waitcnt lgkmcnt(4)
	global_store_dwordx4 v[146:147], v[242:245], off
	v_pk_mul_f32 v[220:221], v[98:99], s[30:31]
	v_exp_f32_e32 v220, v220
	v_exp_f32_e32 v221, v221
	s_nop 0
	v_pk_add_f32 v[220:221], v[220:221], 1.0 op_sel_hi:[1,0]
	v_rcp_f32_e32 v220, v220
	v_rcp_f32_e32 v221, v221
	s_nop 0
	v_pk_mul_f32 v[220:221], v[220:221], v[98:99]
	v_pk_mul_f32 v[220:221], v[220:221], v[90:91]
	v_cvt_pk_bf16_f32 v224, v220, v221
	v_pk_mul_f32 v[220:221], v[100:101], s[30:31]
	v_exp_f32_e32 v220, v220
	v_exp_f32_e32 v221, v221
	s_nop 0
	v_pk_add_f32 v[220:221], v[220:221], 1.0 op_sel_hi:[1,0]
	v_rcp_f32_e32 v220, v220
	v_rcp_f32_e32 v221, v221
	s_nop 0
	v_pk_mul_f32 v[220:221], v[220:221], v[100:101]
	v_pk_mul_f32 v[220:221], v[220:221], v[92:93]
	v_cvt_pk_bf16_f32 v225, v220, v221
	v_pk_mul_f32 v[220:221], v[94:95], s[30:31]
	v_exp_f32_e32 v220, v220
	v_exp_f32_e32 v221, v221
	s_nop 0
	v_pk_add_f32 v[220:221], v[220:221], 1.0 op_sel_hi:[1,0]
	v_rcp_f32_e32 v220, v220
	v_rcp_f32_e32 v221, v221
	s_nop 0
	v_pk_mul_f32 v[220:221], v[220:221], v[94:95]
	v_pk_mul_f32 v[220:221], v[220:221], v[86:87]
	v_cvt_pk_bf16_f32 v226, v220, v221
	v_pk_mul_f32 v[220:221], v[96:97], s[30:31]
	v_exp_f32_e32 v220, v220
	v_exp_f32_e32 v221, v221
	s_nop 0
	v_pk_add_f32 v[220:221], v[220:221], 1.0 op_sel_hi:[1,0]
	v_rcp_f32_e32 v220, v220
	v_rcp_f32_e32 v221, v221
	s_nop 0
	v_pk_mul_f32 v[220:221], v[220:221], v[96:97]
	v_pk_mul_f32 v[220:221], v[220:221], v[88:89]
	v_cvt_pk_bf16_f32 v227, v220, v221
	ds_bpermute_b32 v242, v145, v224
	ds_bpermute_b32 v243, v145, v225
	ds_bpermute_b32 v244, v145, v226
	ds_bpermute_b32 v245, v145, v227
	s_mov_b32 s4, 0x2c00
	s_mov_b32 s5, 0
	v_lshl_add_u64 v[146:147], v[216:217], 0, s[4:5]
	s_waitcnt lgkmcnt(4)
	global_store_dwordx4 v[228:229], v[246:249], off
	v_pk_mul_f32 v[220:221], v[82:83], s[30:31]
	v_exp_f32_e32 v220, v220
	v_exp_f32_e32 v221, v221
	s_nop 0
	v_pk_add_f32 v[220:221], v[220:221], 1.0 op_sel_hi:[1,0]
	v_rcp_f32_e32 v220, v220
	v_rcp_f32_e32 v221, v221
	s_nop 0
	v_pk_mul_f32 v[220:221], v[220:221], v[82:83]
	v_pk_mul_f32 v[220:221], v[220:221], v[74:75]
	v_cvt_pk_bf16_f32 v224, v220, v221
	v_pk_mul_f32 v[220:221], v[84:85], s[30:31]
	v_exp_f32_e32 v220, v220
	v_exp_f32_e32 v221, v221
	s_nop 0
	v_pk_add_f32 v[220:221], v[220:221], 1.0 op_sel_hi:[1,0]
	v_rcp_f32_e32 v220, v220
	v_rcp_f32_e32 v221, v221
	s_nop 0
	v_pk_mul_f32 v[220:221], v[220:221], v[84:85]
	v_pk_mul_f32 v[220:221], v[220:221], v[76:77]
	v_cvt_pk_bf16_f32 v225, v220, v221
	v_pk_mul_f32 v[220:221], v[78:79], s[30:31]
	v_exp_f32_e32 v220, v220
	v_exp_f32_e32 v221, v221
	s_nop 0
	v_pk_add_f32 v[220:221], v[220:221], 1.0 op_sel_hi:[1,0]
	v_rcp_f32_e32 v220, v220
	v_rcp_f32_e32 v221, v221
	s_nop 0
	v_pk_mul_f32 v[220:221], v[220:221], v[78:79]
	v_pk_mul_f32 v[220:221], v[220:221], v[70:71]
	v_cvt_pk_bf16_f32 v226, v220, v221
	v_pk_mul_f32 v[220:221], v[80:81], s[30:31]
	v_exp_f32_e32 v220, v220
	v_exp_f32_e32 v221, v221
	s_nop 0
	v_pk_add_f32 v[220:221], v[220:221], 1.0 op_sel_hi:[1,0]
	v_rcp_f32_e32 v220, v220
	v_rcp_f32_e32 v221, v221
	s_nop 0
	v_pk_mul_f32 v[220:221], v[220:221], v[80:81]
	v_pk_mul_f32 v[220:221], v[220:221], v[72:73]
	v_cvt_pk_bf16_f32 v227, v220, v221
	ds_bpermute_b32 v246, v145, v224
	ds_bpermute_b32 v247, v145, v225
	ds_bpermute_b32 v248, v145, v226
	ds_bpermute_b32 v249, v145, v227
	s_mov_b32 s4, 0x4200
	s_mov_b32 s5, 0
	v_lshl_add_u64 v[228:229], v[216:217], 0, s[4:5]
	s_waitcnt lgkmcnt(4)
	global_store_dwordx4 v[146:147], v[242:245], off
	v_pk_fma_f32 v[220:221], v[66:67], v[168:169], v[176:177]
	v_pk_fma_f32 v[222:223], v[50:51], v[168:169], v[176:177]
	v_fmac_f32_dpp v220, v18, v160 row_shr:1 row_mask:0xf bank_mask:0xf
	v_fmac_f32_dpp v220, v34, v152 row_shr:1 row_mask:0xf bank_mask:0xf
	v_fmac_f32_dpp v222, v18, v152 row_shr:1 row_mask:0xf bank_mask:0xf
	v_fmac_f32_dpp v221, v19, v161 row_shr:1 row_mask:0xf bank_mask:0xf
	v_fmac_f32_dpp v221, v35, v153 row_shr:1 row_mask:0xf bank_mask:0xf
	v_fmac_f32_dpp v223, v19, v153 row_shr:1 row_mask:0xf bank_mask:0xf
	v_pk_fma_f32 v[222:223], v[66:67], v[160:161], v[222:223]
	v_pk_fma_f32 v[18:19], v[18:19], v[168:169], v[176:177]
	v_pk_fma_f32 v[18:19], v[34:35], v[160:161], v[18:19]
	v_pk_fma_f32 v[18:19], v[50:51], v[152:153], v[18:19]
	v_pk_fma_f32 v[34:35], v[34:35], v[168:169], v[176:177]
	v_pk_fma_f32 v[34:35], v[50:51], v[160:161], v[34:35]
	v_pk_fma_f32 v[34:35], v[66:67], v[152:153], v[34:35]
	v_mov_b32_e32 v66, v220
	v_mov_b32_e32 v67, v221
	v_mov_b32_e32 v50, v222
	v_mov_b32_e32 v51, v223
	v_pk_fma_f32 v[220:221], v[68:69], v[170:171], v[178:179]
	v_pk_fma_f32 v[222:223], v[52:53], v[170:171], v[178:179]
	v_fmac_f32_dpp v220, v20, v162 row_shr:1 row_mask:0xf bank_mask:0xf
	v_fmac_f32_dpp v220, v36, v154 row_shr:1 row_mask:0xf bank_mask:0xf
	v_fmac_f32_dpp v222, v20, v154 row_shr:1 row_mask:0xf bank_mask:0xf
	v_fmac_f32_dpp v221, v21, v163 row_shr:1 row_mask:0xf bank_mask:0xf
	v_fmac_f32_dpp v221, v37, v155 row_shr:1 row_mask:0xf bank_mask:0xf
	v_fmac_f32_dpp v223, v21, v155 row_shr:1 row_mask:0xf bank_mask:0xf
	v_pk_fma_f32 v[222:223], v[68:69], v[162:163], v[222:223]
	v_pk_fma_f32 v[20:21], v[20:21], v[170:171], v[178:179]
	v_pk_fma_f32 v[20:21], v[36:37], v[162:163], v[20:21]
	v_pk_fma_f32 v[20:21], v[52:53], v[154:155], v[20:21]
	v_pk_fma_f32 v[36:37], v[36:37], v[170:171], v[178:179]
	v_pk_fma_f32 v[36:37], v[52:53], v[162:163], v[36:37]
	v_pk_fma_f32 v[36:37], v[68:69], v[154:155], v[36:37]
	v_mov_b32_e32 v68, v220
	v_mov_b32_e32 v69, v221
	v_mov_b32_e32 v52, v222
	v_mov_b32_e32 v53, v223
	v_pk_fma_f32 v[220:221], v[62:63], v[172:173], v[180:181]
	v_pk_fma_f32 v[222:223], v[46:47], v[172:173], v[180:181]
	v_fmac_f32_dpp v220, v14, v164 row_shr:1 row_mask:0xf bank_mask:0xf
	v_fmac_f32_dpp v220, v30, v156 row_shr:1 row_mask:0xf bank_mask:0xf
	v_fmac_f32_dpp v222, v14, v156 row_shr:1 row_mask:0xf bank_mask:0xf
	v_fmac_f32_dpp v221, v15, v165 row_shr:1 row_mask:0xf bank_mask:0xf
	v_fmac_f32_dpp v221, v31, v157 row_shr:1 row_mask:0xf bank_mask:0xf
	v_fmac_f32_dpp v223, v15, v157 row_shr:1 row_mask:0xf bank_mask:0xf
	v_pk_fma_f32 v[222:223], v[62:63], v[164:165], v[222:223]
	v_pk_fma_f32 v[14:15], v[14:15], v[172:173], v[180:181]
	v_pk_fma_f32 v[14:15], v[30:31], v[164:165], v[14:15]
	v_pk_fma_f32 v[14:15], v[46:47], v[156:157], v[14:15]
	v_pk_fma_f32 v[30:31], v[30:31], v[172:173], v[180:181]
	v_pk_fma_f32 v[30:31], v[46:47], v[164:165], v[30:31]
	v_pk_fma_f32 v[30:31], v[62:63], v[156:157], v[30:31]
	v_mov_b32_e32 v62, v220
	v_mov_b32_e32 v63, v221
	v_mov_b32_e32 v46, v222
	v_mov_b32_e32 v47, v223
	v_pk_fma_f32 v[220:221], v[64:65], v[174:175], v[182:183]
	v_pk_fma_f32 v[222:223], v[48:49], v[174:175], v[182:183]
	v_fmac_f32_dpp v220, v16, v166 row_shr:1 row_mask:0xf bank_mask:0xf
	v_fmac_f32_dpp v220, v32, v158 row_shr:1 row_mask:0xf bank_mask:0xf
	v_fmac_f32_dpp v222, v16, v158 row_shr:1 row_mask:0xf bank_mask:0xf
	v_fmac_f32_dpp v221, v17, v167 row_shr:1 row_mask:0xf bank_mask:0xf
	v_fmac_f32_dpp v221, v33, v159 row_shr:1 row_mask:0xf bank_mask:0xf
	v_fmac_f32_dpp v223, v17, v159 row_shr:1 row_mask:0xf bank_mask:0xf
	v_pk_fma_f32 v[222:223], v[64:65], v[166:167], v[222:223]
	v_pk_fma_f32 v[16:17], v[16:17], v[174:175], v[182:183]
	v_pk_fma_f32 v[16:17], v[32:33], v[166:167], v[16:17]
	v_pk_fma_f32 v[16:17], v[48:49], v[158:159], v[16:17]
	v_pk_fma_f32 v[32:33], v[32:33], v[174:175], v[182:183]
	v_pk_fma_f32 v[32:33], v[48:49], v[166:167], v[32:33]
	v_pk_fma_f32 v[32:33], v[64:65], v[158:159], v[32:33]
	v_mov_b32_e32 v64, v220
	v_mov_b32_e32 v65, v221
	v_mov_b32_e32 v48, v222
	v_mov_b32_e32 v49, v223
	v_pk_fma_f32 v[220:221], v[58:59], v[200:201], v[208:209]
	v_pk_fma_f32 v[222:223], v[42:43], v[200:201], v[208:209]
	v_fmac_f32_dpp v220, v10, v192 row_shr:1 row_mask:0xf bank_mask:0xf
	v_fmac_f32_dpp v220, v26, v184 row_shr:1 row_mask:0xf bank_mask:0xf
	v_fmac_f32_dpp v222, v10, v184 row_shr:1 row_mask:0xf bank_mask:0xf
	v_fmac_f32_dpp v221, v11, v193 row_shr:1 row_mask:0xf bank_mask:0xf
	v_fmac_f32_dpp v221, v27, v185 row_shr:1 row_mask:0xf bank_mask:0xf
	v_fmac_f32_dpp v223, v11, v185 row_shr:1 row_mask:0xf bank_mask:0xf
	v_pk_fma_f32 v[222:223], v[58:59], v[192:193], v[222:223]
	v_pk_fma_f32 v[10:11], v[10:11], v[200:201], v[208:209]
	v_pk_fma_f32 v[10:11], v[26:27], v[192:193], v[10:11]
	v_pk_fma_f32 v[10:11], v[42:43], v[184:185], v[10:11]
	v_pk_fma_f32 v[26:27], v[26:27], v[200:201], v[208:209]
	v_pk_fma_f32 v[26:27], v[42:43], v[192:193], v[26:27]
	v_pk_fma_f32 v[26:27], v[58:59], v[184:185], v[26:27]
	v_mov_b32_e32 v58, v220
	v_mov_b32_e32 v59, v221
	v_mov_b32_e32 v42, v222
	v_mov_b32_e32 v43, v223
	v_pk_fma_f32 v[220:221], v[60:61], v[202:203], v[210:211]
	v_pk_fma_f32 v[222:223], v[44:45], v[202:203], v[210:211]
	v_fmac_f32_dpp v220, v12, v194 row_shr:1 row_mask:0xf bank_mask:0xf
	v_fmac_f32_dpp v220, v28, v186 row_shr:1 row_mask:0xf bank_mask:0xf
	v_fmac_f32_dpp v222, v12, v186 row_shr:1 row_mask:0xf bank_mask:0xf
	v_fmac_f32_dpp v221, v13, v195 row_shr:1 row_mask:0xf bank_mask:0xf
	v_fmac_f32_dpp v221, v29, v187 row_shr:1 row_mask:0xf bank_mask:0xf
	v_fmac_f32_dpp v223, v13, v187 row_shr:1 row_mask:0xf bank_mask:0xf
	v_pk_fma_f32 v[222:223], v[60:61], v[194:195], v[222:223]
	v_pk_fma_f32 v[12:13], v[12:13], v[202:203], v[210:211]
	v_pk_fma_f32 v[12:13], v[28:29], v[194:195], v[12:13]
	v_pk_fma_f32 v[12:13], v[44:45], v[186:187], v[12:13]
	v_pk_fma_f32 v[28:29], v[28:29], v[202:203], v[210:211]
	v_pk_fma_f32 v[28:29], v[44:45], v[194:195], v[28:29]
	v_pk_fma_f32 v[28:29], v[60:61], v[186:187], v[28:29]
	v_mov_b32_e32 v60, v220
	v_mov_b32_e32 v61, v221
	v_mov_b32_e32 v44, v222
	v_mov_b32_e32 v45, v223
	v_pk_fma_f32 v[220:221], v[54:55], v[204:205], v[212:213]
	v_pk_fma_f32 v[222:223], v[38:39], v[204:205], v[212:213]
	v_fmac_f32_dpp v220, v6, v196 row_shr:1 row_mask:0xf bank_mask:0xf
	v_fmac_f32_dpp v220, v22, v188 row_shr:1 row_mask:0xf bank_mask:0xf
	v_fmac_f32_dpp v222, v6, v188 row_shr:1 row_mask:0xf bank_mask:0xf
	v_fmac_f32_dpp v221, v7, v197 row_shr:1 row_mask:0xf bank_mask:0xf
	v_fmac_f32_dpp v221, v23, v189 row_shr:1 row_mask:0xf bank_mask:0xf
	v_fmac_f32_dpp v223, v7, v189 row_shr:1 row_mask:0xf bank_mask:0xf
	v_pk_fma_f32 v[222:223], v[54:55], v[196:197], v[222:223]
	v_pk_fma_f32 v[6:7], v[6:7], v[204:205], v[212:213]
	v_pk_fma_f32 v[6:7], v[22:23], v[196:197], v[6:7]
	v_pk_fma_f32 v[6:7], v[38:39], v[188:189], v[6:7]
	v_pk_fma_f32 v[22:23], v[22:23], v[204:205], v[212:213]
	v_pk_fma_f32 v[22:23], v[38:39], v[196:197], v[22:23]
	v_pk_fma_f32 v[22:23], v[54:55], v[188:189], v[22:23]
	v_mov_b32_e32 v54, v220
	v_mov_b32_e32 v55, v221
	v_mov_b32_e32 v38, v222
	v_mov_b32_e32 v39, v223
	v_pk_fma_f32 v[220:221], v[56:57], v[206:207], v[214:215]
	v_pk_fma_f32 v[222:223], v[40:41], v[206:207], v[214:215]
	v_fmac_f32_dpp v220, v8, v198 row_shr:1 row_mask:0xf bank_mask:0xf
	v_fmac_f32_dpp v220, v24, v190 row_shr:1 row_mask:0xf bank_mask:0xf
	v_fmac_f32_dpp v222, v8, v190 row_shr:1 row_mask:0xf bank_mask:0xf
	v_fmac_f32_dpp v221, v9, v199 row_shr:1 row_mask:0xf bank_mask:0xf
	v_fmac_f32_dpp v221, v25, v191 row_shr:1 row_mask:0xf bank_mask:0xf
	v_fmac_f32_dpp v223, v9, v191 row_shr:1 row_mask:0xf bank_mask:0xf
	v_pk_fma_f32 v[222:223], v[56:57], v[198:199], v[222:223]
	v_pk_fma_f32 v[8:9], v[8:9], v[206:207], v[214:215]
	v_pk_fma_f32 v[8:9], v[24:25], v[198:199], v[8:9]
	v_pk_fma_f32 v[8:9], v[40:41], v[190:191], v[8:9]
	v_pk_fma_f32 v[24:25], v[24:25], v[206:207], v[214:215]
	v_pk_fma_f32 v[24:25], v[40:41], v[198:199], v[24:25]
	v_pk_fma_f32 v[24:25], v[56:57], v[190:191], v[24:25]
	v_mov_b32_e32 v56, v220
	v_mov_b32_e32 v57, v221
	v_mov_b32_e32 v40, v222
	v_mov_b32_e32 v41, v223
	v_pk_mul_f32 v[220:221], v[66:67], s[30:31]
	v_exp_f32_e32 v220, v220
	v_exp_f32_e32 v221, v221
	s_nop 0
	v_pk_add_f32 v[220:221], v[220:221], 1.0 op_sel_hi:[1,0]
	v_rcp_f32_e32 v220, v220
	v_rcp_f32_e32 v221, v221
	s_nop 0
	v_pk_mul_f32 v[220:221], v[220:221], v[66:67]
	v_pk_mul_f32 v[220:221], v[220:221], v[58:59]
	v_cvt_pk_bf16_f32 v224, v220, v221
	v_pk_mul_f32 v[220:221], v[68:69], s[30:31]
	v_exp_f32_e32 v220, v220
	v_exp_f32_e32 v221, v221
	s_nop 0
	v_pk_add_f32 v[220:221], v[220:221], 1.0 op_sel_hi:[1,0]
	v_rcp_f32_e32 v220, v220
	v_rcp_f32_e32 v221, v221
	s_nop 0
	v_pk_mul_f32 v[220:221], v[220:221], v[68:69]
	v_pk_mul_f32 v[220:221], v[220:221], v[60:61]
	v_cvt_pk_bf16_f32 v225, v220, v221
	v_pk_mul_f32 v[220:221], v[62:63], s[30:31]
	v_exp_f32_e32 v220, v220
	v_exp_f32_e32 v221, v221
	s_nop 0
	v_pk_add_f32 v[220:221], v[220:221], 1.0 op_sel_hi:[1,0]
	v_rcp_f32_e32 v220, v220
	v_rcp_f32_e32 v221, v221
	s_nop 0
	v_pk_mul_f32 v[220:221], v[220:221], v[62:63]
	v_pk_mul_f32 v[220:221], v[220:221], v[54:55]
	v_cvt_pk_bf16_f32 v226, v220, v221
	v_pk_mul_f32 v[220:221], v[64:65], s[30:31]
	v_exp_f32_e32 v220, v220
	v_exp_f32_e32 v221, v221
	s_nop 0
	v_pk_add_f32 v[220:221], v[220:221], 1.0 op_sel_hi:[1,0]
	v_rcp_f32_e32 v220, v220
	v_rcp_f32_e32 v221, v221
	s_nop 0
	v_pk_mul_f32 v[220:221], v[220:221], v[64:65]
	v_pk_mul_f32 v[220:221], v[220:221], v[56:57]
	v_cvt_pk_bf16_f32 v227, v220, v221
	ds_bpermute_b32 v242, v145, v224
	ds_bpermute_b32 v243, v145, v225
	ds_bpermute_b32 v244, v145, v226
	ds_bpermute_b32 v245, v145, v227
	s_mov_b32 s4, 0xb0000
	s_mov_b32 s5, 0
	v_lshl_add_u64 v[146:147], v[216:217], 0, s[4:5]
	s_waitcnt lgkmcnt(4)
	global_store_dwordx4 v[228:229], v[246:249], off
	v_pk_mul_f32 v[220:221], v[50:51], s[30:31]
	v_exp_f32_e32 v220, v220
	v_exp_f32_e32 v221, v221
	s_nop 0
	v_pk_add_f32 v[220:221], v[220:221], 1.0 op_sel_hi:[1,0]
	v_rcp_f32_e32 v220, v220
	v_rcp_f32_e32 v221, v221
	s_nop 0
	v_pk_mul_f32 v[220:221], v[220:221], v[50:51]
	v_pk_mul_f32 v[220:221], v[220:221], v[42:43]
	v_cvt_pk_bf16_f32 v224, v220, v221
	v_pk_mul_f32 v[220:221], v[52:53], s[30:31]
	v_exp_f32_e32 v220, v220
	v_exp_f32_e32 v221, v221
	s_nop 0
	v_pk_add_f32 v[220:221], v[220:221], 1.0 op_sel_hi:[1,0]
	v_rcp_f32_e32 v220, v220
	v_rcp_f32_e32 v221, v221
	s_nop 0
	v_pk_mul_f32 v[220:221], v[220:221], v[52:53]
	v_pk_mul_f32 v[220:221], v[220:221], v[44:45]
	v_cvt_pk_bf16_f32 v225, v220, v221
	v_pk_mul_f32 v[220:221], v[46:47], s[30:31]
	v_exp_f32_e32 v220, v220
	v_exp_f32_e32 v221, v221
	s_nop 0
	v_pk_add_f32 v[220:221], v[220:221], 1.0 op_sel_hi:[1,0]
	v_rcp_f32_e32 v220, v220
	v_rcp_f32_e32 v221, v221
	s_nop 0
	v_pk_mul_f32 v[220:221], v[220:221], v[46:47]
	v_pk_mul_f32 v[220:221], v[220:221], v[38:39]
	v_cvt_pk_bf16_f32 v226, v220, v221
	v_pk_mul_f32 v[220:221], v[48:49], s[30:31]
	v_exp_f32_e32 v220, v220
	v_exp_f32_e32 v221, v221
	s_nop 0
	v_pk_add_f32 v[220:221], v[220:221], 1.0 op_sel_hi:[1,0]
	v_rcp_f32_e32 v220, v220
	v_rcp_f32_e32 v221, v221
	s_nop 0
	v_pk_mul_f32 v[220:221], v[220:221], v[48:49]
	v_pk_mul_f32 v[220:221], v[220:221], v[40:41]
	v_cvt_pk_bf16_f32 v227, v220, v221
	ds_bpermute_b32 v246, v145, v224
	ds_bpermute_b32 v247, v145, v225
	ds_bpermute_b32 v248, v145, v226
	ds_bpermute_b32 v249, v145, v227
	s_mov_b32 s4, 0xb1600
	s_mov_b32 s5, 0
	v_lshl_add_u64 v[228:229], v[216:217], 0, s[4:5]
	s_waitcnt lgkmcnt(4)
	global_store_dwordx4 v[146:147], v[242:245], off
	v_pk_mul_f32 v[220:221], v[34:35], s[30:31]
	v_exp_f32_e32 v220, v220
	v_exp_f32_e32 v221, v221
	s_nop 0
	v_pk_add_f32 v[220:221], v[220:221], 1.0 op_sel_hi:[1,0]
	v_rcp_f32_e32 v220, v220
	v_rcp_f32_e32 v221, v221
	s_nop 0
	v_pk_mul_f32 v[220:221], v[220:221], v[34:35]
	v_pk_mul_f32 v[220:221], v[220:221], v[26:27]
	v_cvt_pk_bf16_f32 v224, v220, v221
	v_pk_mul_f32 v[220:221], v[36:37], s[30:31]
	v_exp_f32_e32 v220, v220
	v_exp_f32_e32 v221, v221
	s_nop 0
	v_pk_add_f32 v[220:221], v[220:221], 1.0 op_sel_hi:[1,0]
	v_rcp_f32_e32 v220, v220
	v_rcp_f32_e32 v221, v221
	s_nop 0
	v_pk_mul_f32 v[220:221], v[220:221], v[36:37]
	v_pk_mul_f32 v[220:221], v[220:221], v[28:29]
	v_cvt_pk_bf16_f32 v225, v220, v221
	v_pk_mul_f32 v[220:221], v[30:31], s[30:31]
	v_exp_f32_e32 v220, v220
	v_exp_f32_e32 v221, v221
	s_nop 0
	v_pk_add_f32 v[220:221], v[220:221], 1.0 op_sel_hi:[1,0]
	v_rcp_f32_e32 v220, v220
	v_rcp_f32_e32 v221, v221
	s_nop 0
	v_pk_mul_f32 v[220:221], v[220:221], v[30:31]
	v_pk_mul_f32 v[220:221], v[220:221], v[22:23]
	v_cvt_pk_bf16_f32 v226, v220, v221
	v_pk_mul_f32 v[220:221], v[32:33], s[30:31]
	v_exp_f32_e32 v220, v220
	v_exp_f32_e32 v221, v221
	s_nop 0
	v_pk_add_f32 v[220:221], v[220:221], 1.0 op_sel_hi:[1,0]
	v_rcp_f32_e32 v220, v220
	v_rcp_f32_e32 v221, v221
	s_nop 0
	v_pk_mul_f32 v[220:221], v[220:221], v[32:33]
	v_pk_mul_f32 v[220:221], v[220:221], v[24:25]
	v_cvt_pk_bf16_f32 v227, v220, v221
	ds_bpermute_b32 v242, v145, v224
	ds_bpermute_b32 v243, v145, v225
	ds_bpermute_b32 v244, v145, v226
	ds_bpermute_b32 v245, v145, v227
	s_mov_b32 s4, 0xb2c00
	s_mov_b32 s5, 0
	v_lshl_add_u64 v[146:147], v[216:217], 0, s[4:5]
	s_waitcnt lgkmcnt(4)
	global_store_dwordx4 v[228:229], v[246:249], off
	v_pk_mul_f32 v[220:221], v[18:19], s[30:31]
	v_exp_f32_e32 v220, v220
	v_exp_f32_e32 v221, v221
	s_nop 0
	v_pk_add_f32 v[220:221], v[220:221], 1.0 op_sel_hi:[1,0]
	v_rcp_f32_e32 v220, v220
	v_rcp_f32_e32 v221, v221
	s_nop 0
	v_pk_mul_f32 v[220:221], v[220:221], v[18:19]
	v_pk_mul_f32 v[220:221], v[220:221], v[10:11]
	v_cvt_pk_bf16_f32 v224, v220, v221
	v_pk_mul_f32 v[220:221], v[20:21], s[30:31]
	v_exp_f32_e32 v220, v220
	v_exp_f32_e32 v221, v221
	s_nop 0
	v_pk_add_f32 v[220:221], v[220:221], 1.0 op_sel_hi:[1,0]
	v_rcp_f32_e32 v220, v220
	v_rcp_f32_e32 v221, v221
	s_nop 0
	v_pk_mul_f32 v[220:221], v[220:221], v[20:21]
	v_pk_mul_f32 v[220:221], v[220:221], v[12:13]
	v_cvt_pk_bf16_f32 v225, v220, v221
	v_pk_mul_f32 v[220:221], v[14:15], s[30:31]
	v_exp_f32_e32 v220, v220
	v_exp_f32_e32 v221, v221
	s_nop 0
	v_pk_add_f32 v[220:221], v[220:221], 1.0 op_sel_hi:[1,0]
	v_rcp_f32_e32 v220, v220
	v_rcp_f32_e32 v221, v221
	s_nop 0
	v_pk_mul_f32 v[220:221], v[220:221], v[14:15]
	v_pk_mul_f32 v[220:221], v[220:221], v[6:7]
	v_cvt_pk_bf16_f32 v226, v220, v221
	v_pk_mul_f32 v[220:221], v[16:17], s[30:31]
	v_exp_f32_e32 v220, v220
	v_exp_f32_e32 v221, v221
	s_nop 0
	v_pk_add_f32 v[220:221], v[220:221], 1.0 op_sel_hi:[1,0]
	v_rcp_f32_e32 v220, v220
	v_rcp_f32_e32 v221, v221
	s_nop 0
	v_pk_mul_f32 v[220:221], v[220:221], v[16:17]
	v_pk_mul_f32 v[220:221], v[220:221], v[8:9]
	v_cvt_pk_bf16_f32 v227, v220, v221
	ds_bpermute_b32 v246, v145, v224
	ds_bpermute_b32 v247, v145, v225
	ds_bpermute_b32 v248, v145, v226
	ds_bpermute_b32 v249, v145, v227
	s_mov_b32 s4, 0xb4200
	s_mov_b32 s5, 0
	v_lshl_add_u64 v[228:229], v[216:217], 0, s[4:5]
	s_waitcnt lgkmcnt(4)
	global_store_dwordx4 v[146:147], v[242:245], off
	s_waitcnt lgkmcnt(0)
	global_store_dwordx4 v[228:229], v[246:249], off
	s_branch .Lup_epi_done
